# outproj0 epilogue: next residual load issued before the previous store, wait relaxed to vmcnt(1)
# speedup vs baseline: 1.0002x; 1.0001x over previous
; DI unsigned cvtpk(float lo, float hi) { f32x2_t v = {lo, hi}; bf16x2_t b = __builtin_convertvector(v, bf16x2_t); return __builtin_bit_cast(unsigned, b); }
;   DI void operator()(const f32x4 (&acc)[2][2][4][2], const pg8::Unit& u, int wr, int wc, int fr, int fq) const {
;     ...
;     for (int ai = 0; ai < 2; ++ai)
; #pragma unroll
;       for (int m = 0; m < 4; ++m) {
;         const int row = u.pm * 256 + ai * 128 + wr * 64 + m * 16 + fr; float rs = 0.f;
; #pragma unroll
;         for (int bj = 0; bj < 2; ++bj)
; #pragma unroll
;           for (int n = 0; n < 2; ++n) {
;             const int col = u.pn * 256 + bj * 128 + wc * 32 + n * 16 + fq * 4; const size_t off = (size_t)row * DM + col;
;             f32x4 xb;
;             if (xin16) { const u32x2 hw = *(const u32x2*)(xin16 + off); xb.x = __uint_as_float(hw.x << 16); xb.y = __uint_as_float(hw.x & 0xffff0000u); xb.z = __uint_as_float(hw.y << 16); xb.w = __uint_as_float(hw.y & 0xffff0000u); }
;             else xb = *(const f32x4*)(xin + off);
;             const f32x4 xn = xb + acc[ai][bj][m][n];
;             { u32x2 wx; wx.x = cvtpk(xn.x, xn.y); wx.y = cvtpk(xn.z, xn.w); *(u32x2*)(X1B + off) = wx; }
;             rs += xn.x * xn.x + xn.y * xn.y + xn.z * xn.z + xn.w * xn.w;
;           }
;         rs += __shfl_xor(rs, 16); rs += __shfl_xor(rs, 32);
;         if (fq == 0) atomicAdd(ss + row, rs);
;         asm volatile("" ::: "memory");
.LBB0_2256:
	v_lshl_add_u32 v142, s0, 8, v144
	v_lshl_or_b32 v140, s2, 8, v146
	v_ashrrev_i32_e32 v143, 31, v142
	v_lshlrev_b64 v[154:155], 10, v[142:143]
	v_ashrrev_i32_e32 v141, 31, v140
	v_lshl_add_u64 v[156:157], v[154:155], 0, v[140:141]
	v_lshl_add_u64 v[158:159], v[156:157], 2, s[10:11]
	global_load_dwordx4 v[150:153], v[158:159], off
	v_lshl_add_u64 v[156:157], v[156:157], 1, s[14:15]
	s_waitcnt vmcnt(0)
	v_pk_add_f32 v[126:127], v[126:127], v[152:153]
	v_pk_add_f32 v[160:161], v[124:125], v[150:151]
	v_cvt_pk_bf16_f32 v125, v126, v127
	v_cvt_pk_bf16_f32 v124, v160, v161
	global_load_dwordx4 v[150:153], v[158:159], off offset:64
	global_store_dwordx2 v[156:157], v[124:125], off
	v_or_b32_e32 v124, 16, v140
	v_ashrrev_i32_e32 v125, 31, v124
	v_lshl_add_u64 v[156:157], v[154:155], 0, v[124:125]
	v_lshl_add_u64 v[156:157], v[156:157], 1, s[14:15]
	s_waitcnt vmcnt(1)
	v_pk_add_f32 v[122:123], v[122:123], v[152:153]
	v_pk_add_f32 v[162:163], v[120:121], v[150:151]
	v_cvt_pk_bf16_f32 v121, v122, v123
	v_cvt_pk_bf16_f32 v120, v162, v163
	global_load_dwordx4 v[150:153], v[158:159], off offset:512
	global_store_dwordx2 v[156:157], v[120:121], off
	v_or_b32_e32 v120, 0x80, v140
	v_ashrrev_i32_e32 v121, 31, v120
	v_lshl_add_u64 v[156:157], v[154:155], 0, v[120:121]
	v_lshl_add_u64 v[156:157], v[156:157], 1, s[14:15]
	s_waitcnt vmcnt(1)
	v_pk_add_f32 v[118:119], v[118:119], v[152:153]
	v_pk_add_f32 v[164:165], v[116:117], v[150:151]
	v_cvt_pk_bf16_f32 v117, v118, v119
	v_cvt_pk_bf16_f32 v116, v164, v165
	global_store_dwordx2 v[156:157], v[116:117], off
	global_load_dwordx4 v[150:153], v[158:159], off offset:576
	v_and_b32_e32 v117, 64, v183
	v_xor_b32_e32 v116, 16, v183
	v_add_u32_e32 v117, 64, v117
	v_xor_b32_e32 v156, 32, v183
	v_cmp_lt_i32_e32 vcc, v116, v117
	s_nop 1
	v_cndmask_b32_e32 v116, v183, v116, vcc
	v_cmp_lt_i32_e32 vcc, v156, v117
	v_lshlrev_b32_e32 v116, 2, v116
	s_nop 0
	v_cndmask_b32_e32 v117, v183, v156, vcc
	v_mul_f32_e32 v156, v161, v161
	v_fmac_f32_e32 v156, v160, v160
	v_fmac_f32_e32 v156, v126, v126
	v_mul_f32_e32 v126, v163, v163
	v_fmac_f32_e32 v126, v162, v162
	v_fmac_f32_e32 v126, v122, v122
	v_fmac_f32_e32 v126, v123, v123
	v_mul_f32_e32 v123, v165, v165
	v_fmac_f32_e32 v123, v164, v164
	v_fmac_f32_e32 v156, v127, v127
	v_fmac_f32_e32 v123, v118, v118
	v_add_f32_e32 v122, v156, v126
	v_fmac_f32_e32 v123, v119, v119
	v_add_f32_e32 v126, v122, v123
	v_lshlrev_b32_e32 v117, 2, v117
	s_waitcnt vmcnt(0)
	v_pk_add_f32 v[122:123], v[112:113], v[150:151]
	s_nop 0
	v_mul_f32_e32 v112, v123, v123
	v_pk_add_f32 v[118:119], v[114:115], v[152:153]
	v_fmac_f32_e32 v112, v122, v122
	v_fmac_f32_e32 v112, v118, v118
	v_fmac_f32_e32 v112, v119, v119
	v_add_f32_e32 v114, v126, v112
	v_mov_b32_e32 v115, v114
	s_nop 1
	v_permlane16_swap_b32_e32 v114, v115
	v_or_b32_e32 v112, 0x90, v140
	v_ashrrev_i32_e32 v113, 31, v112
	v_lshl_add_u64 v[126:127], v[154:155], 0, v[112:113]
	v_cvt_pk_bf16_f32 v122, v122, v123
	s_waitcnt lgkmcnt(0)
	v_add_f32_e32 v114, v114, v115
	ds_bpermute_b32 v115, v117, v114
	v_cvt_pk_bf16_f32 v123, v118, v119
	v_lshl_add_u64 v[118:119], v[126:127], 1, s[14:15]
	global_store_dwordx2 v[118:119], v[122:123], off
	s_and_saveexec_b64 s[0:1], s[6:7]
	s_cbranch_execz .LBB0_2258
	s_waitcnt lgkmcnt(0)
	v_add_f32_e32 v118, v114, v115
	v_lshl_add_u64 v[114:115], v[142:143], 2, s[16:17]
	global_atomic_add_f32 v[114:115], v118, off
.LBB0_2258:
	s_or_b64 exec, exec, s[0:1]
	v_or_b32_e32 v114, 16, v142
	s_waitcnt lgkmcnt(0)
	v_ashrrev_i32_e32 v115, 31, v114
	v_lshlrev_b64 v[118:119], 10, v[114:115]
	v_lshl_add_u64 v[122:123], v[118:119], 0, v[140:141]
	v_lshl_add_u64 v[126:127], v[122:123], 2, s[10:11]
	global_load_dwordx4 v[150:153], v[126:127], off
	v_lshl_add_u64 v[122:123], v[122:123], 1, s[14:15]
	s_waitcnt vmcnt(0)
	v_pk_add_f32 v[152:153], v[110:111], v[152:153]
	v_pk_add_f32 v[150:151], v[108:109], v[150:151]
	v_cvt_pk_bf16_f32 v109, v152, v153
	v_cvt_pk_bf16_f32 v108, v150, v151
	global_load_dwordx4 v[108:111], v[126:127], off offset:64
	global_store_dwordx2 v[122:123], v[108:109], off
	v_lshl_add_u64 v[122:123], v[118:119], 0, v[124:125]
	v_lshl_add_u64 v[122:123], v[122:123], 1, s[14:15]
	s_waitcnt vmcnt(1)
	v_pk_add_f32 v[110:111], v[106:107], v[110:111]
	v_pk_add_f32 v[108:109], v[104:105], v[108:109]
	v_cvt_pk_bf16_f32 v105, v110, v111
	v_cvt_pk_bf16_f32 v104, v108, v109
	global_load_dwordx4 v[104:107], v[126:127], off offset:512
	global_store_dwordx2 v[122:123], v[104:105], off
	v_lshl_add_u64 v[122:123], v[118:119], 0, v[120:121]
	v_lshl_add_u64 v[122:123], v[122:123], 1, s[14:15]
	v_mul_f32_e32 v109, v109, v109
	v_fmac_f32_e32 v109, v108, v108
	v_fmac_f32_e32 v109, v110, v110
	v_fmac_f32_e32 v109, v111, v111
	s_waitcnt vmcnt(1)
	v_pk_add_f32 v[106:107], v[102:103], v[106:107]
	v_pk_add_f32 v[104:105], v[100:101], v[104:105]
	v_cvt_pk_bf16_f32 v101, v106, v107
	v_cvt_pk_bf16_f32 v100, v104, v105
	global_load_dwordx4 v[100:103], v[126:127], off offset:576
	global_store_dwordx2 v[122:123], v[100:101], off
	v_mul_f32_e32 v122, v151, v151
	v_fmac_f32_e32 v122, v150, v150
	v_mul_f32_e32 v105, v105, v105
	v_fmac_f32_e32 v122, v152, v152
	v_fmac_f32_e32 v105, v104, v104
	v_fmac_f32_e32 v122, v153, v153
	v_fmac_f32_e32 v105, v106, v106
	v_add_f32_e32 v108, v122, v109
	v_fmac_f32_e32 v105, v107, v107
	v_add_f32_e32 v104, v108, v105
	s_waitcnt vmcnt(1)
	v_pk_add_f32 v[100:101], v[96:97], v[100:101]
	s_nop 0
	v_mul_f32_e32 v96, v101, v101
	v_pk_add_f32 v[98:99], v[98:99], v[102:103]
	v_fmac_f32_e32 v96, v100, v100
	v_fmac_f32_e32 v96, v98, v98
	v_fmac_f32_e32 v96, v99, v99
	v_add_f32_e32 v96, v104, v96
	ds_bpermute_b32 v97, v116, v96
	v_lshl_add_u64 v[102:103], v[118:119], 0, v[112:113]
	v_cvt_pk_bf16_f32 v100, v100, v101
	v_cvt_pk_bf16_f32 v101, v98, v99
	v_lshl_add_u64 v[98:99], v[102:103], 1, s[14:15]
	s_waitcnt lgkmcnt(0)
	v_add_f32_e32 v96, v96, v97
	ds_bpermute_b32 v97, v117, v96
	global_store_dwordx2 v[98:99], v[100:101], off
	s_and_saveexec_b64 s[0:1], s[6:7]
	s_cbranch_execz .LBB0_2260
	s_waitcnt lgkmcnt(0)
	v_add_f32_e32 v98, v96, v97
	v_lshl_add_u64 v[96:97], v[114:115], 2, s[16:17]
	global_atomic_add_f32 v[96:97], v98, off
; DI unsigned cvtpk(float lo, float hi) { f32x2_t v = {lo, hi}; bf16x2_t b = __builtin_convertvector(v, bf16x2_t); return __builtin_bit_cast(unsigned, b); }
;   DI void operator()(const f32x4 (&acc)[2][2][4][2], const pg8::Unit& u, int wr, int wc, int fr, int fq) const {
;     ...
;     for (int ai = 0; ai < 2; ++ai)
; #pragma unroll
;       for (int m = 0; m < 4; ++m) {
;         const int row = u.pm * 256 + ai * 128 + wr * 64 + m * 16 + fr; float rs = 0.f;
; #pragma unroll
;         for (int bj = 0; bj < 2; ++bj)
; #pragma unroll
;           for (int n = 0; n < 2; ++n) {
;             const int col = u.pn * 256 + bj * 128 + wc * 32 + n * 16 + fq * 4; const size_t off = (size_t)row * DM + col;
;             f32x4 xb;
;             if (xin16) { const u32x2 hw = *(const u32x2*)(xin16 + off); xb.x = __uint_as_float(hw.x << 16); xb.y = __uint_as_float(hw.x & 0xffff0000u); xb.z = __uint_as_float(hw.y << 16); xb.w = __uint_as_float(hw.y & 0xffff0000u); }
;             else xb = *(const f32x4*)(xin + off);
;             const f32x4 xn = xb + acc[ai][bj][m][n];
;             { u32x2 wx; wx.x = cvtpk(xn.x, xn.y); wx.y = cvtpk(xn.z, xn.w); *(u32x2*)(X1B + off) = wx; }
;             rs += xn.x * xn.x + xn.y * xn.y + xn.z * xn.z + xn.w * xn.w;
;           }
;         rs += __shfl_xor(rs, 16); rs += __shfl_xor(rs, 32);
;         if (fq == 0) atomicAdd(ss + row, rs);
;         asm volatile("" ::: "memory");
.LBB0_2260:
	s_or_b64 exec, exec, s[0:1]
	v_or_b32_e32 v96, 32, v142
	s_waitcnt lgkmcnt(0)
	v_ashrrev_i32_e32 v97, 31, v96
	v_lshlrev_b64 v[102:103], 10, v[96:97]
	v_lshl_add_u64 v[104:105], v[102:103], 0, v[140:141]
	v_lshl_add_u64 v[106:107], v[104:105], 2, s[10:11]
	global_load_dwordx4 v[98:101], v[106:107], off
	v_lshl_add_u64 v[104:105], v[104:105], 1, s[14:15]
	s_waitcnt vmcnt(0)
	v_pk_add_f32 v[100:101], v[94:95], v[100:101]
	v_pk_add_f32 v[98:99], v[92:93], v[98:99]
	v_cvt_pk_bf16_f32 v93, v100, v101
	v_cvt_pk_bf16_f32 v92, v98, v99
	global_load_dwordx4 v[92:95], v[106:107], off offset:64
	global_store_dwordx2 v[104:105], v[92:93], off
	v_lshl_add_u64 v[104:105], v[102:103], 0, v[124:125]
	v_lshl_add_u64 v[104:105], v[104:105], 1, s[14:15]
	v_mul_f32_e32 v99, v99, v99
	v_fmac_f32_e32 v99, v98, v98
	v_fmac_f32_e32 v99, v100, v100
	v_fmac_f32_e32 v99, v101, v101
	s_waitcnt vmcnt(1)
	v_pk_add_f32 v[94:95], v[90:91], v[94:95]
	v_pk_add_f32 v[92:93], v[88:89], v[92:93]
	v_cvt_pk_bf16_f32 v89, v94, v95
	v_cvt_pk_bf16_f32 v88, v92, v93
	global_load_dwordx4 v[88:91], v[106:107], off offset:512
	global_store_dwordx2 v[104:105], v[88:89], off
	v_lshl_add_u64 v[104:105], v[102:103], 0, v[120:121]
	v_lshl_add_u64 v[104:105], v[104:105], 1, s[14:15]
	v_mul_f32_e32 v93, v93, v93
	v_fmac_f32_e32 v93, v92, v92
	v_fmac_f32_e32 v93, v94, v94
	v_fmac_f32_e32 v93, v95, v95
	v_add_f32_e32 v92, v99, v93
	s_waitcnt vmcnt(1)
	v_pk_add_f32 v[90:91], v[86:87], v[90:91]
	v_pk_add_f32 v[88:89], v[84:85], v[88:89]
	v_cvt_pk_bf16_f32 v85, v90, v91
	v_cvt_pk_bf16_f32 v84, v88, v89
	global_load_dwordx4 v[84:87], v[106:107], off offset:576
	global_store_dwordx2 v[104:105], v[84:85], off
	v_mul_f32_e32 v89, v89, v89
	v_fmac_f32_e32 v89, v88, v88
	v_fmac_f32_e32 v89, v90, v90
	v_fmac_f32_e32 v89, v91, v91
	v_add_f32_e32 v88, v92, v89
	s_waitcnt vmcnt(1)
	v_pk_add_f32 v[84:85], v[80:81], v[84:85]
	s_nop 0
	v_mul_f32_e32 v80, v85, v85
	v_pk_add_f32 v[82:83], v[82:83], v[86:87]
	v_fmac_f32_e32 v80, v84, v84
	v_fmac_f32_e32 v80, v82, v82
	v_fmac_f32_e32 v80, v83, v83
	v_add_f32_e32 v80, v88, v80
	ds_bpermute_b32 v81, v116, v80
	v_lshl_add_u64 v[86:87], v[102:103], 0, v[112:113]
	v_cvt_pk_bf16_f32 v84, v84, v85
	v_cvt_pk_bf16_f32 v85, v82, v83
	v_lshl_add_u64 v[82:83], v[86:87], 1, s[14:15]
	s_waitcnt lgkmcnt(0)
	v_add_f32_e32 v80, v80, v81
	ds_bpermute_b32 v81, v117, v80
	global_store_dwordx2 v[82:83], v[84:85], off
	s_and_saveexec_b64 s[0:1], s[6:7]
	s_cbranch_execz .LBB0_2262
	s_waitcnt lgkmcnt(0)
	v_add_f32_e32 v82, v80, v81
	v_lshl_add_u64 v[80:81], v[96:97], 2, s[16:17]
	global_atomic_add_f32 v[80:81], v82, off
.LBB0_2262:
	s_or_b64 exec, exec, s[0:1]
	v_or_b32_e32 v80, 48, v142
	s_waitcnt lgkmcnt(0)
	v_ashrrev_i32_e32 v81, 31, v80
	v_lshlrev_b64 v[86:87], 10, v[80:81]
	v_lshl_add_u64 v[88:89], v[86:87], 0, v[140:141]
	v_lshl_add_u64 v[90:91], v[88:89], 2, s[10:11]
	global_load_dwordx4 v[82:85], v[90:91], off
	v_lshl_add_u64 v[88:89], v[88:89], 1, s[14:15]
	s_waitcnt vmcnt(0)
	v_pk_add_f32 v[84:85], v[78:79], v[84:85]
	v_pk_add_f32 v[82:83], v[76:77], v[82:83]
	v_cvt_pk_bf16_f32 v77, v84, v85
	v_cvt_pk_bf16_f32 v76, v82, v83
	global_load_dwordx4 v[76:79], v[90:91], off offset:64
	global_store_dwordx2 v[88:89], v[76:77], off
	v_lshl_add_u64 v[88:89], v[86:87], 0, v[124:125]
	v_lshl_add_u64 v[88:89], v[88:89], 1, s[14:15]
	v_mul_f32_e32 v83, v83, v83
	v_fmac_f32_e32 v83, v82, v82
	v_fmac_f32_e32 v83, v84, v84
	v_fmac_f32_e32 v83, v85, v85
	s_waitcnt vmcnt(1)
	v_pk_add_f32 v[78:79], v[74:75], v[78:79]
	v_pk_add_f32 v[76:77], v[72:73], v[76:77]
	v_cvt_pk_bf16_f32 v73, v78, v79
	v_cvt_pk_bf16_f32 v72, v76, v77
	global_load_dwordx4 v[72:75], v[90:91], off offset:512
	global_store_dwordx2 v[88:89], v[72:73], off
	v_lshl_add_u64 v[88:89], v[86:87], 0, v[120:121]
	v_lshl_add_u64 v[88:89], v[88:89], 1, s[14:15]
	v_mul_f32_e32 v77, v77, v77
	v_fmac_f32_e32 v77, v76, v76
	v_fmac_f32_e32 v77, v78, v78
	v_fmac_f32_e32 v77, v79, v79
	v_add_f32_e32 v76, v83, v77
	s_waitcnt vmcnt(1)
	v_pk_add_f32 v[74:75], v[70:71], v[74:75]
	v_pk_add_f32 v[72:73], v[68:69], v[72:73]
	v_cvt_pk_bf16_f32 v69, v74, v75
	v_cvt_pk_bf16_f32 v68, v72, v73
	global_load_dwordx4 v[68:71], v[90:91], off offset:576
	global_store_dwordx2 v[88:89], v[68:69], off
	v_mul_f32_e32 v73, v73, v73
	v_fmac_f32_e32 v73, v72, v72
	v_fmac_f32_e32 v73, v74, v74
	v_fmac_f32_e32 v73, v75, v75
	v_add_f32_e32 v72, v76, v73
	s_waitcnt vmcnt(1)
	v_pk_add_f32 v[68:69], v[64:65], v[68:69]
	s_nop 0
	v_mul_f32_e32 v64, v69, v69
	v_pk_add_f32 v[66:67], v[66:67], v[70:71]
	v_fmac_f32_e32 v64, v68, v68
	v_fmac_f32_e32 v64, v66, v66
	v_fmac_f32_e32 v64, v67, v67
	v_add_f32_e32 v64, v72, v64
	ds_bpermute_b32 v65, v116, v64
	v_lshl_add_u64 v[70:71], v[86:87], 0, v[112:113]
	v_cvt_pk_bf16_f32 v68, v68, v69
	v_cvt_pk_bf16_f32 v69, v66, v67
	v_lshl_add_u64 v[66:67], v[70:71], 1, s[14:15]
	s_waitcnt lgkmcnt(0)
	v_add_f32_e32 v64, v64, v65
	ds_bpermute_b32 v65, v117, v64
	global_store_dwordx2 v[66:67], v[68:69], off
	s_and_saveexec_b64 s[0:1], s[6:7]
	s_cbranch_execz .LBB0_2264
	s_waitcnt lgkmcnt(0)
	v_add_f32_e32 v66, v64, v65
	v_lshl_add_u64 v[64:65], v[80:81], 2, s[16:17]
	global_atomic_add_f32 v[64:65], v66, off
; DI unsigned cvtpk(float lo, float hi) { f32x2_t v = {lo, hi}; bf16x2_t b = __builtin_convertvector(v, bf16x2_t); return __builtin_bit_cast(unsigned, b); }
;   DI void operator()(const f32x4 (&acc)[2][2][4][2], const pg8::Unit& u, int wr, int wc, int fr, int fq) const {
;     ...
;     for (int ai = 0; ai < 2; ++ai)
; #pragma unroll
;       for (int m = 0; m < 4; ++m) {
;         const int row = u.pm * 256 + ai * 128 + wr * 64 + m * 16 + fr; float rs = 0.f;
; #pragma unroll
;         for (int bj = 0; bj < 2; ++bj)
; #pragma unroll
;           for (int n = 0; n < 2; ++n) {
;             const int col = u.pn * 256 + bj * 128 + wc * 32 + n * 16 + fq * 4; const size_t off = (size_t)row * DM + col;
;             f32x4 xb;
;             if (xin16) { const u32x2 hw = *(const u32x2*)(xin16 + off); xb.x = __uint_as_float(hw.x << 16); xb.y = __uint_as_float(hw.x & 0xffff0000u); xb.z = __uint_as_float(hw.y << 16); xb.w = __uint_as_float(hw.y & 0xffff0000u); }
;             else xb = *(const f32x4*)(xin + off);
;             const f32x4 xn = xb + acc[ai][bj][m][n];
;             { u32x2 wx; wx.x = cvtpk(xn.x, xn.y); wx.y = cvtpk(xn.z, xn.w); *(u32x2*)(X1B + off) = wx; }
;             rs += xn.x * xn.x + xn.y * xn.y + xn.z * xn.z + xn.w * xn.w;
;           }
;         rs += __shfl_xor(rs, 16); rs += __shfl_xor(rs, 32);
;         if (fq == 0) atomicAdd(ss + row, rs);
;         asm volatile("" ::: "memory");
.LBB0_2264:
	s_or_b64 exec, exec, s[0:1]
	v_add_u32_e32 v64, 0x80, v142
	s_waitcnt lgkmcnt(0)
	v_ashrrev_i32_e32 v65, 31, v64
	v_lshlrev_b64 v[70:71], 10, v[64:65]
	v_lshl_add_u64 v[72:73], v[70:71], 0, v[140:141]
	v_lshl_add_u64 v[74:75], v[72:73], 2, s[10:11]
	global_load_dwordx4 v[66:69], v[74:75], off
	v_lshl_add_u64 v[72:73], v[72:73], 1, s[14:15]
	s_waitcnt vmcnt(0)
	v_pk_add_f32 v[68:69], v[62:63], v[68:69]
	v_pk_add_f32 v[66:67], v[60:61], v[66:67]
	v_cvt_pk_bf16_f32 v61, v68, v69
	v_cvt_pk_bf16_f32 v60, v66, v67
	global_load_dwordx4 v[60:63], v[74:75], off offset:64
	global_store_dwordx2 v[72:73], v[60:61], off
	v_lshl_add_u64 v[72:73], v[70:71], 0, v[124:125]
	v_lshl_add_u64 v[72:73], v[72:73], 1, s[14:15]
	v_mul_f32_e32 v67, v67, v67
	v_fmac_f32_e32 v67, v66, v66
	v_fmac_f32_e32 v67, v68, v68
	v_fmac_f32_e32 v67, v69, v69
	s_waitcnt vmcnt(1)
	v_pk_add_f32 v[62:63], v[58:59], v[62:63]
	v_pk_add_f32 v[60:61], v[56:57], v[60:61]
	v_cvt_pk_bf16_f32 v57, v62, v63
	v_cvt_pk_bf16_f32 v56, v60, v61
	global_load_dwordx4 v[56:59], v[74:75], off offset:512
	global_store_dwordx2 v[72:73], v[56:57], off
	v_lshl_add_u64 v[72:73], v[70:71], 0, v[120:121]
	v_lshl_add_u64 v[72:73], v[72:73], 1, s[14:15]
	v_mul_f32_e32 v61, v61, v61
	v_fmac_f32_e32 v61, v60, v60
	v_fmac_f32_e32 v61, v62, v62
	v_fmac_f32_e32 v61, v63, v63
	v_add_f32_e32 v60, v67, v61
	s_waitcnt vmcnt(1)
	v_pk_add_f32 v[58:59], v[54:55], v[58:59]
	v_pk_add_f32 v[56:57], v[52:53], v[56:57]
	v_cvt_pk_bf16_f32 v53, v58, v59
	v_cvt_pk_bf16_f32 v52, v56, v57
	global_load_dwordx4 v[52:55], v[74:75], off offset:576
	global_store_dwordx2 v[72:73], v[52:53], off
	v_mul_f32_e32 v57, v57, v57
	v_fmac_f32_e32 v57, v56, v56
	v_fmac_f32_e32 v57, v58, v58
	v_fmac_f32_e32 v57, v59, v59
	v_add_f32_e32 v56, v60, v57
	s_waitcnt vmcnt(1)
	v_pk_add_f32 v[52:53], v[48:49], v[52:53]
	s_nop 0
	v_mul_f32_e32 v48, v53, v53
	v_pk_add_f32 v[50:51], v[50:51], v[54:55]
	v_fmac_f32_e32 v48, v52, v52
	v_fmac_f32_e32 v48, v50, v50
	v_fmac_f32_e32 v48, v51, v51
	v_add_f32_e32 v48, v56, v48
	ds_bpermute_b32 v49, v116, v48
	v_lshl_add_u64 v[54:55], v[70:71], 0, v[112:113]
	v_cvt_pk_bf16_f32 v52, v52, v53
	v_cvt_pk_bf16_f32 v53, v50, v51
	v_lshl_add_u64 v[50:51], v[54:55], 1, s[14:15]
	s_waitcnt lgkmcnt(0)
	v_add_f32_e32 v48, v48, v49
	ds_bpermute_b32 v49, v117, v48
	global_store_dwordx2 v[50:51], v[52:53], off
	s_and_saveexec_b64 s[0:1], s[6:7]
	s_cbranch_execz .LBB0_2266
	s_waitcnt lgkmcnt(0)
	v_add_f32_e32 v50, v48, v49
	v_lshl_add_u64 v[48:49], v[64:65], 2, s[16:17]
	global_atomic_add_f32 v[48:49], v50, off
.LBB0_2266:
	s_or_b64 exec, exec, s[0:1]
	v_add_u32_e32 v48, 0x90, v142
	s_waitcnt lgkmcnt(0)
	v_ashrrev_i32_e32 v49, 31, v48
	v_lshlrev_b64 v[54:55], 10, v[48:49]
	v_lshl_add_u64 v[56:57], v[54:55], 0, v[140:141]
	v_lshl_add_u64 v[58:59], v[56:57], 2, s[10:11]
	global_load_dwordx4 v[50:53], v[58:59], off
	v_lshl_add_u64 v[56:57], v[56:57], 1, s[14:15]
	s_waitcnt vmcnt(0)
	v_pk_add_f32 v[52:53], v[46:47], v[52:53]
	v_pk_add_f32 v[50:51], v[44:45], v[50:51]
	v_cvt_pk_bf16_f32 v45, v52, v53
	v_cvt_pk_bf16_f32 v44, v50, v51
	global_load_dwordx4 v[44:47], v[58:59], off offset:64
	global_store_dwordx2 v[56:57], v[44:45], off
	v_lshl_add_u64 v[56:57], v[54:55], 0, v[124:125]
	v_lshl_add_u64 v[56:57], v[56:57], 1, s[14:15]
	v_mul_f32_e32 v51, v51, v51
	v_fmac_f32_e32 v51, v50, v50
	v_fmac_f32_e32 v51, v52, v52
	v_fmac_f32_e32 v51, v53, v53
	s_waitcnt vmcnt(1)
	v_pk_add_f32 v[46:47], v[42:43], v[46:47]
	v_pk_add_f32 v[44:45], v[40:41], v[44:45]
	v_cvt_pk_bf16_f32 v41, v46, v47
	v_cvt_pk_bf16_f32 v40, v44, v45
	global_load_dwordx4 v[40:43], v[58:59], off offset:512
	global_store_dwordx2 v[56:57], v[40:41], off
	v_lshl_add_u64 v[56:57], v[54:55], 0, v[120:121]
	v_lshl_add_u64 v[56:57], v[56:57], 1, s[14:15]
	v_mul_f32_e32 v45, v45, v45
	v_fmac_f32_e32 v45, v44, v44
	v_fmac_f32_e32 v45, v46, v46
	v_fmac_f32_e32 v45, v47, v47
	v_add_f32_e32 v44, v51, v45
	s_waitcnt vmcnt(1)
	v_pk_add_f32 v[42:43], v[38:39], v[42:43]
	v_pk_add_f32 v[40:41], v[36:37], v[40:41]
	v_cvt_pk_bf16_f32 v37, v42, v43
	v_cvt_pk_bf16_f32 v36, v40, v41
	global_load_dwordx4 v[36:39], v[58:59], off offset:576
	global_store_dwordx2 v[56:57], v[36:37], off
	v_mul_f32_e32 v41, v41, v41
	v_fmac_f32_e32 v41, v40, v40
	v_fmac_f32_e32 v41, v42, v42
	v_fmac_f32_e32 v41, v43, v43
	v_add_f32_e32 v40, v44, v41
	s_waitcnt vmcnt(1)
	v_pk_add_f32 v[36:37], v[32:33], v[36:37]
	s_nop 0
	v_mul_f32_e32 v32, v37, v37
	v_pk_add_f32 v[34:35], v[34:35], v[38:39]
	v_fmac_f32_e32 v32, v36, v36
	v_fmac_f32_e32 v32, v34, v34
	v_fmac_f32_e32 v32, v35, v35
	v_add_f32_e32 v32, v40, v32
	ds_bpermute_b32 v33, v116, v32
	v_lshl_add_u64 v[38:39], v[54:55], 0, v[112:113]
	v_cvt_pk_bf16_f32 v36, v36, v37
	v_cvt_pk_bf16_f32 v37, v34, v35
	v_lshl_add_u64 v[34:35], v[38:39], 1, s[14:15]
	s_waitcnt lgkmcnt(0)
	v_add_f32_e32 v32, v32, v33
	ds_bpermute_b32 v33, v117, v32
	global_store_dwordx2 v[34:35], v[36:37], off
	s_and_saveexec_b64 s[0:1], s[6:7]
	s_cbranch_execz .LBB0_2268
	s_waitcnt lgkmcnt(0)
	v_add_f32_e32 v34, v32, v33
	v_lshl_add_u64 v[32:33], v[48:49], 2, s[16:17]
	global_atomic_add_f32 v[32:33], v34, off
; DI unsigned cvtpk(float lo, float hi) { f32x2_t v = {lo, hi}; bf16x2_t b = __builtin_convertvector(v, bf16x2_t); return __builtin_bit_cast(unsigned, b); }
;   DI void operator()(const f32x4 (&acc)[2][2][4][2], const pg8::Unit& u, int wr, int wc, int fr, int fq) const {
;     ...
;     for (int ai = 0; ai < 2; ++ai)
; #pragma unroll
;       for (int m = 0; m < 4; ++m) {
;         const int row = u.pm * 256 + ai * 128 + wr * 64 + m * 16 + fr; float rs = 0.f;
; #pragma unroll
;         for (int bj = 0; bj < 2; ++bj)
; #pragma unroll
;           for (int n = 0; n < 2; ++n) {
;             const int col = u.pn * 256 + bj * 128 + wc * 32 + n * 16 + fq * 4; const size_t off = (size_t)row * DM + col;
;             f32x4 xb;
;             if (xin16) { const u32x2 hw = *(const u32x2*)(xin16 + off); xb.x = __uint_as_float(hw.x << 16); xb.y = __uint_as_float(hw.x & 0xffff0000u); xb.z = __uint_as_float(hw.y << 16); xb.w = __uint_as_float(hw.y & 0xffff0000u); }
;             else xb = *(const f32x4*)(xin + off);
;             const f32x4 xn = xb + acc[ai][bj][m][n];
;             { u32x2 wx; wx.x = cvtpk(xn.x, xn.y); wx.y = cvtpk(xn.z, xn.w); *(u32x2*)(X1B + off) = wx; }
;             rs += xn.x * xn.x + xn.y * xn.y + xn.z * xn.z + xn.w * xn.w;
;           }
;         rs += __shfl_xor(rs, 16); rs += __shfl_xor(rs, 32);
;         if (fq == 0) atomicAdd(ss + row, rs);
;         asm volatile("" ::: "memory");
.LBB0_2268:
	s_or_b64 exec, exec, s[0:1]
	v_add_u32_e32 v32, 0xa0, v142
	s_waitcnt lgkmcnt(0)
	v_ashrrev_i32_e32 v33, 31, v32
	v_lshlrev_b64 v[38:39], 10, v[32:33]
	v_lshl_add_u64 v[40:41], v[38:39], 0, v[140:141]
	v_lshl_add_u64 v[42:43], v[40:41], 2, s[10:11]
	global_load_dwordx4 v[34:37], v[42:43], off
	v_lshl_add_u64 v[40:41], v[40:41], 1, s[14:15]
	s_waitcnt vmcnt(0)
	v_pk_add_f32 v[36:37], v[30:31], v[36:37]
	v_pk_add_f32 v[34:35], v[28:29], v[34:35]
	v_cvt_pk_bf16_f32 v29, v36, v37
	v_cvt_pk_bf16_f32 v28, v34, v35
	global_load_dwordx4 v[28:31], v[42:43], off offset:64
	global_store_dwordx2 v[40:41], v[28:29], off
	v_lshl_add_u64 v[40:41], v[38:39], 0, v[124:125]
	v_lshl_add_u64 v[40:41], v[40:41], 1, s[14:15]
	v_mul_f32_e32 v35, v35, v35
	v_fmac_f32_e32 v35, v34, v34
	v_fmac_f32_e32 v35, v36, v36
	v_fmac_f32_e32 v35, v37, v37
	s_waitcnt vmcnt(1)
	v_pk_add_f32 v[30:31], v[26:27], v[30:31]
	v_pk_add_f32 v[28:29], v[24:25], v[28:29]
	v_cvt_pk_bf16_f32 v25, v30, v31
	v_cvt_pk_bf16_f32 v24, v28, v29
	global_load_dwordx4 v[24:27], v[42:43], off offset:512
	global_store_dwordx2 v[40:41], v[24:25], off
	v_lshl_add_u64 v[40:41], v[38:39], 0, v[120:121]
	v_lshl_add_u64 v[40:41], v[40:41], 1, s[14:15]
	v_mul_f32_e32 v29, v29, v29
	v_fmac_f32_e32 v29, v28, v28
	v_fmac_f32_e32 v29, v30, v30
	v_fmac_f32_e32 v29, v31, v31
	v_add_f32_e32 v28, v35, v29
	s_waitcnt vmcnt(1)
	v_pk_add_f32 v[26:27], v[22:23], v[26:27]
	v_pk_add_f32 v[24:25], v[20:21], v[24:25]
	v_cvt_pk_bf16_f32 v21, v26, v27
	v_cvt_pk_bf16_f32 v20, v24, v25
	global_load_dwordx4 v[20:23], v[42:43], off offset:576
	global_store_dwordx2 v[40:41], v[20:21], off
	v_mul_f32_e32 v25, v25, v25
	v_fmac_f32_e32 v25, v24, v24
	v_fmac_f32_e32 v25, v26, v26
	v_fmac_f32_e32 v25, v27, v27
	v_add_f32_e32 v24, v28, v25
	s_waitcnt vmcnt(1)
	v_pk_add_f32 v[20:21], v[16:17], v[20:21]
	s_nop 0
	v_mul_f32_e32 v16, v21, v21
	v_pk_add_f32 v[18:19], v[18:19], v[22:23]
	v_fmac_f32_e32 v16, v20, v20
	v_fmac_f32_e32 v16, v18, v18
	v_fmac_f32_e32 v16, v19, v19
	v_add_f32_e32 v16, v24, v16
	ds_bpermute_b32 v17, v116, v16
	v_lshl_add_u64 v[22:23], v[38:39], 0, v[112:113]
	v_cvt_pk_bf16_f32 v20, v20, v21
	v_cvt_pk_bf16_f32 v21, v18, v19
	v_lshl_add_u64 v[18:19], v[22:23], 1, s[14:15]
	s_waitcnt lgkmcnt(0)
	v_add_f32_e32 v16, v16, v17
	ds_bpermute_b32 v17, v117, v16
	global_store_dwordx2 v[18:19], v[20:21], off
	s_and_saveexec_b64 s[0:1], s[6:7]
	s_cbranch_execz .LBB0_2270
	s_waitcnt lgkmcnt(0)
	v_add_f32_e32 v18, v16, v17
	v_lshl_add_u64 v[16:17], v[32:33], 2, s[16:17]
	global_atomic_add_f32 v[16:17], v18, off
.LBB0_2270:
	s_or_b64 exec, exec, s[0:1]
	v_add_u32_e32 v16, 0xb0, v142
	s_waitcnt lgkmcnt(0)
	v_ashrrev_i32_e32 v17, 31, v16
	v_lshlrev_b64 v[22:23], 10, v[16:17]
	v_lshl_add_u64 v[24:25], v[22:23], 0, v[140:141]
	v_lshl_add_u64 v[26:27], v[24:25], 2, s[10:11]
	global_load_dwordx4 v[18:21], v[26:27], off
	v_lshl_add_u64 v[24:25], v[24:25], 1, s[14:15]
	s_waitcnt vmcnt(0)
	v_pk_add_f32 v[20:21], v[14:15], v[20:21]
	v_pk_add_f32 v[18:19], v[12:13], v[18:19]
	v_cvt_pk_bf16_f32 v13, v20, v21
	v_cvt_pk_bf16_f32 v12, v18, v19
	global_load_dwordx4 v[12:15], v[26:27], off offset:64
	global_store_dwordx2 v[24:25], v[12:13], off
	v_lshl_add_u64 v[24:25], v[22:23], 0, v[124:125]
	v_lshl_add_u64 v[24:25], v[24:25], 1, s[14:15]
	v_mul_f32_e32 v19, v19, v19
	v_fmac_f32_e32 v19, v18, v18
	v_fmac_f32_e32 v19, v20, v20
	v_fmac_f32_e32 v19, v21, v21
	s_waitcnt vmcnt(1)
	v_pk_add_f32 v[14:15], v[10:11], v[14:15]
	v_pk_add_f32 v[12:13], v[8:9], v[12:13]
	v_cvt_pk_bf16_f32 v9, v14, v15
	v_cvt_pk_bf16_f32 v8, v12, v13
	global_load_dwordx4 v[8:11], v[26:27], off offset:512
	global_store_dwordx2 v[24:25], v[8:9], off
	v_lshl_add_u64 v[24:25], v[22:23], 0, v[120:121]
	v_lshl_add_u64 v[24:25], v[24:25], 1, s[14:15]
	v_mul_f32_e32 v13, v13, v13
	v_fmac_f32_e32 v13, v12, v12
	v_fmac_f32_e32 v13, v14, v14
	v_fmac_f32_e32 v13, v15, v15
	v_add_f32_e32 v12, v19, v13
	s_waitcnt vmcnt(1)
	v_pk_add_f32 v[10:11], v[6:7], v[10:11]
	v_pk_add_f32 v[8:9], v[4:5], v[8:9]
	v_cvt_pk_bf16_f32 v5, v10, v11
	v_cvt_pk_bf16_f32 v4, v8, v9
	global_load_dwordx4 v[4:7], v[26:27], off offset:576
	global_store_dwordx2 v[24:25], v[4:5], off
	v_mul_f32_e32 v9, v9, v9
	v_fmac_f32_e32 v9, v8, v8
	v_fmac_f32_e32 v9, v10, v10
	v_fmac_f32_e32 v9, v11, v11
	v_add_f32_e32 v8, v12, v9
	s_waitcnt vmcnt(1)
	v_pk_add_f32 v[4:5], v[0:1], v[4:5]
	s_nop 0
	v_mul_f32_e32 v0, v5, v5
	v_pk_add_f32 v[2:3], v[2:3], v[6:7]
	v_fmac_f32_e32 v0, v4, v4
	v_fmac_f32_e32 v0, v2, v2
	v_fmac_f32_e32 v0, v3, v3
	v_add_f32_e32 v0, v8, v0
	ds_bpermute_b32 v1, v116, v0
	v_lshl_add_u64 v[6:7], v[22:23], 0, v[112:113]
	v_cvt_pk_bf16_f32 v4, v4, v5
	v_cvt_pk_bf16_f32 v5, v2, v3
	v_lshl_add_u64 v[2:3], v[6:7], 1, s[14:15]
	s_waitcnt lgkmcnt(0)
	v_add_f32_e32 v0, v0, v1
	ds_bpermute_b32 v1, v117, v0
	global_store_dwordx2 v[2:3], v[4:5], off
	s_and_saveexec_b64 s[0:1], s[6:7]
	s_cbranch_execz .LBB0_2272
	s_waitcnt lgkmcnt(0)
	v_add_f32_e32 v2, v0, v1
	v_lshl_add_u64 v[0:1], v[16:17], 2, s[16:17]
	global_atomic_add_f32 v[0:1], v2, off
